# w_in GEMM phase: workgroups with blockIdx bit 3 start about 4us later to de-synchronise epilogue store bursts
# speedup vs baseline: 1.0068x; 1.0032x over previous
.LBB0_232:
	s_or_b64 exec, exec, s[0:1]
	v_mov_b32_e32 v8, v254
	s_bitcmp0_b32 s2, 3
	s_cbranch_scc1 .Lstg2_go
	s_sleep 64
	s_sleep 64
.Lstg2_go:
	s_cmpk_lt_i32 s2, 0xa00
	s_waitcnt lgkmcnt(0)
	s_barrier
	s_cselect_b64 s[4:5], -1, 0
	s_cmpk_gt_i32 s2, 0x9ff
	v_readfirstlane_b32 s3, v8
	s_cbranch_scc1 .LBB0_234
	s_ashr_i32 s0, s2, 31
	s_lshr_b32 s0, s0, 29
	s_add_i32 s0, s2, s0
	s_ashr_i32 s1, s0, 3
	s_and_b32 s0, s0, -8
	s_sub_i32 s0, s2, s0
	s_cmp_lt_i32 s0, 0
	s_movk_i32 s6, 0x141
	s_cselect_b32 s6, s6, 0x140
	s_mul_i32 s0, s6, s0
	s_add_i32 s0, s0, s1
	s_mul_hi_i32 s1, s0, 0x66666667
	s_lshr_b32 s6, s1, 31
	s_ashr_i32 s1, s1, 6
	s_add_i32 s1, s1, s6
	s_lshl_b32 s6, s1, 3
	s_mulk_i32 s1, 0xa0
	s_sub_i32 s0, s0, s1
	s_sext_i32_i16 s1, s0
	s_bfe_u32 s1, s1, 0x3001c
	s_add_i32 s1, s0, s1
	s_sext_i32_i16 s7, s1
	s_and_b32 s1, s1, 0xfff8
	s_sub_i32 s0, s0, s1
	s_sext_i32_i16 s0, s0
	s_add_i32 s60, s6, s0
	s_ashr_i32 s0, s7, 3
